# FFN-up K loop: half of the LDS-DMA loads use SGPR-base + 32-bit VGPR offset addressing instead of a 64-bit VALU add
# baseline (speedup 1.0000x reference)
.LBB0_554:
	s_add_i32 s68, s68, 1
	s_mul_i32 s2, s68, s18
	s_add_i32 s10, s2, s20
	s_cmp_lt_i32 s10, s19
	s_cselect_b64 s[2:3], -1, 0
	s_cmp_ge_i32 s10, s19
	s_cselect_b64 s[38:39], -1, 0
	s_and_b64 s[6:7], s[2:3], exec
	s_cselect_b32 s6, s10, 0
	s_ashr_i32 s7, s6, 31
	s_lshr_b32 s7, s7, 29
	s_add_i32 s7, s6, s7
	s_ashr_i32 s10, s7, 3
	s_and_b32 s7, s7, -8
	s_sub_i32 s6, s6, s7
	s_cmp_lt_i32 s6, 0
	s_cselect_b32 s7, s61, s60
	s_mul_i32 s6, s7, s6
	s_add_i32 s10, s6, s10
	s_mul_hi_i32 s6, s10, 0x2e8ba2e9
	s_lshr_b32 s7, s6, 31
	s_ashr_i32 s6, s6, 4
	s_add_i32 s24, s6, s7
	s_lshl_b32 s25, s24, 2
	s_sub_i32 s6, s9, s25
	s_min_i32 s41, s6, 4
	s_abs_i32 s40, s41
	v_cvt_f32_u32_e32 v0, s40
	s_mov_b64 s[6:7], s[34:35]
	s_mov_b64 s[54:55], s[36:37]
	s_sub_i32 s35, 0, s40
	v_rcp_iflag_f32_e32 v0, v0
	s_mulk_i32 s24, 0x58
	s_sub_i32 s10, s10, s24
	s_abs_i32 s34, s10
	v_mul_f32_e32 v0, 0x4f7ffffe, v0
	v_cvt_u32_f32_e32 v0, v0
	s_xor_b32 s24, s10, s41
	s_ashr_i32 s24, s24, 31
	s_mov_b32 s73, -2
	v_readfirstlane_b32 s36, v0
	s_mul_i32 s35, s35, s36
	s_mul_hi_u32 s35, s36, s35
	s_add_i32 s36, s36, s35
	s_mul_hi_u32 s35, s34, s36
	s_mul_i32 s36, s35, s40
	s_sub_i32 s34, s34, s36
	s_add_i32 s36, s35, 1
	s_sub_i32 s37, s34, s40
	s_cmp_ge_u32 s34, s40
	s_cselect_b32 s35, s36, s35
	s_cselect_b32 s34, s37, s34
	s_add_i32 s36, s35, 1
	s_cmp_ge_u32 s34, s40
	s_cselect_b32 s34, s36, s35
	s_xor_b32 s34, s34, s24
	s_sub_i32 s40, s34, s24
	s_mul_i32 s24, s40, s41
	s_sub_i32 s10, s10, s24
	s_add_i32 s42, s25, s10
	s_ashr_i32 s43, s42, 31
	s_lshl_b64 s[24:25], s[42:43], 19
	s_add_u32 s34, s58, s24
	s_addc_u32 s35, s59, s25
	s_and_b64 s[24:25], s[2:3], exec
	s_cselect_b32 s10, s35, s7
	s_cselect_b32 s24, s34, s6
	s_ashr_i32 s41, s40, 31
	s_lshl_b64 s[36:37], s[40:41], 19
	s_add_u32 s36, s44, s36
	s_addc_u32 s37, s45, s37
	s_and_b64 s[2:3], s[2:3], exec
	s_cselect_b32 s25, s37, s55
	s_cselect_b32 s41, s36, s54
	s_add_u32 s43, s54, 0x100
	s_addc_u32 s69, s55, 0
	s_add_u32 s6, s6, 0x40080
	s_addc_u32 s7, s7, 0
	s_add_u32 s2, s6, 0xfffc0080
	s_addc_u32 s3, s7, -1
	s_add_i32 s77, 0, 0x10000
	v_add_u32_e32 v150, s77, v139
	ds_read_b128 v[134:137], v150
	ds_read_b128 v[142:145], v150 offset:1024
	ds_read_b128 v[146:149], v150 offset:2048
	ds_read_b128 v[150:153], v150 offset:3072
	s_cmp_eq_u32 s73, 12
	s_cselect_b32 s3, s10, s3
	s_cselect_b32 s2, s24, s2
	s_cselect_b32 s55, s25, s69
	s_cselect_b32 s54, s41, s43
	s_add_i32 m0, s47, 0xc000
	ds_read_b128 v[162:165], v141
	ds_read_b128 v[166:169], v141 offset:1024
	ds_read_b128 v[170:173], v141 offset:2048
	ds_read_b128 v[174:177], v141 offset:3072
	ds_read_b128 v[178:181], v141 offset:4096
	ds_read_b128 v[182:185], v141 offset:5120
	ds_read_b128 v[186:189], v141 offset:6144
	ds_read_b128 v[214:217], v141 offset:7168
	global_load_lds_dwordx4 v132, s[6:7]
	s_add_i32 m0, s47, 0xe000
	s_nop 0
	global_load_lds_dwordx4 v130, s[6:7]
	s_waitcnt lgkmcnt(8)
	s_barrier
	s_waitcnt lgkmcnt(0)
	s_setprio 1
	s_waitcnt lgkmcnt(0)
	v_mfma_f32_16x16x32_bf16 v[124:127], v[134:137], v[162:165], 0
	v_mfma_f32_16x16x32_bf16 v[116:119], v[146:149], v[162:165], 0
	v_mfma_f32_16x16x32_bf16 v[108:111], v[134:137], v[170:173], 0
	v_mfma_f32_16x16x32_bf16 v[100:103], v[146:149], v[170:173], 0
	v_mfma_f32_16x16x32_bf16 v[92:95], v[134:137], v[178:181], 0
	v_mfma_f32_16x16x32_bf16 v[84:87], v[146:149], v[178:181], 0
	v_mfma_f32_16x16x32_bf16 v[76:79], v[134:137], v[186:189], 0
	v_mfma_f32_16x16x32_bf16 v[68:71], v[146:149], v[186:189], 0
	v_mfma_f32_16x16x32_bf16 v[124:127], v[142:145], v[166:169], v[124:127]
	v_mfma_f32_16x16x32_bf16 v[116:119], v[150:153], v[166:169], v[116:119]
	v_mfma_f32_16x16x32_bf16 v[108:111], v[142:145], v[174:177], v[108:111]
	v_mfma_f32_16x16x32_bf16 v[100:103], v[150:153], v[174:177], v[100:103]
	v_mfma_f32_16x16x32_bf16 v[92:95], v[142:145], v[182:185], v[92:95]
	v_mfma_f32_16x16x32_bf16 v[84:87], v[150:153], v[182:185], v[84:87]
	v_mfma_f32_16x16x32_bf16 v[76:79], v[142:145], v[214:217], v[76:79]
	v_mfma_f32_16x16x32_bf16 v[68:71], v[150:153], v[214:217], v[68:71]
	s_setprio 0
	s_barrier
	s_add_i32 s80, 0, 0x14000
	v_add_u32_e32 v154, s80, v139
	s_add_i32 s77, s77, s53
	ds_read_b128 v[218:221], v154
	ds_read_b128 v[222:225], v154 offset:1024
	ds_read_b128 v[226:229], v154 offset:2048
	ds_read_b128 v[230:233], v154 offset:3072
	v_lshl_add_u64 v[154:155], s[54:55], 0, v[156:157]
	s_mov_b32 m0, s77
	v_lshl_add_u64 v[206:207], s[54:55], 0, v[128:129]
	global_load_lds_dwordx4 v[154:155], off
	s_add_i32 m0, s77, 0x2000
	s_nop 0
	global_load_lds_dwordx4 v[206:207], off
	s_barrier
	s_waitcnt lgkmcnt(0)
	s_setprio 1
	s_waitcnt lgkmcnt(0)
	v_mfma_f32_16x16x32_bf16 v[120:123], v[218:221], v[162:165], 0
	v_mfma_f32_16x16x32_bf16 v[112:115], v[226:229], v[162:165], 0
	v_mfma_f32_16x16x32_bf16 v[104:107], v[218:221], v[170:173], 0
	v_mfma_f32_16x16x32_bf16 v[96:99], v[226:229], v[170:173], 0
	v_mfma_f32_16x16x32_bf16 v[88:91], v[218:221], v[178:181], 0
	v_mfma_f32_16x16x32_bf16 v[80:83], v[226:229], v[178:181], 0
	v_mfma_f32_16x16x32_bf16 v[72:75], v[218:221], v[186:189], 0
	v_mfma_f32_16x16x32_bf16 v[64:67], v[226:229], v[186:189], 0
	v_mfma_f32_16x16x32_bf16 v[120:123], v[222:225], v[166:169], v[120:123]
	v_mfma_f32_16x16x32_bf16 v[112:115], v[230:233], v[166:169], v[112:115]
	v_mfma_f32_16x16x32_bf16 v[104:107], v[222:225], v[174:177], v[104:107]
	v_mfma_f32_16x16x32_bf16 v[96:99], v[230:233], v[174:177], v[96:99]
	v_mfma_f32_16x16x32_bf16 v[88:91], v[222:225], v[182:185], v[88:91]
	v_mfma_f32_16x16x32_bf16 v[80:83], v[230:233], v[182:185], v[80:83]
	v_mfma_f32_16x16x32_bf16 v[72:75], v[222:225], v[214:217], v[72:75]
	v_mfma_f32_16x16x32_bf16 v[64:67], v[230:233], v[214:217], v[64:67]
	s_setprio 0
	s_mov_b32 m0, s47
	v_lshl_add_u64 v[208:209], s[2:3], 0, v[156:157]
	s_barrier
	ds_read_b128 v[162:165], v141 offset:16384
	ds_read_b128 v[166:169], v141 offset:17408
	ds_read_b128 v[170:173], v141 offset:18432
	ds_read_b128 v[174:177], v141 offset:19456
	ds_read_b128 v[178:181], v141 offset:20480
	ds_read_b128 v[182:185], v141 offset:21504
	ds_read_b128 v[186:189], v141 offset:22528
	ds_read_b128 v[214:217], v141 offset:23552
	global_load_lds_dwordx4 v[208:209], off
	v_lshl_add_u64 v[234:235], s[2:3], 0, v[128:129]
	s_mov_b32 m0, s49
	s_nop 0
	global_load_lds_dwordx4 v[234:235], off
	s_barrier
	s_waitcnt lgkmcnt(0)
	s_setprio 1
	s_waitcnt lgkmcnt(0)
	v_mfma_f32_16x16x32_bf16 v[60:63], v[134:137], v[162:165], 0
	v_mfma_f32_16x16x32_bf16 v[52:55], v[146:149], v[162:165], 0
	v_mfma_f32_16x16x32_bf16 v[44:47], v[134:137], v[170:173], 0
	v_mfma_f32_16x16x32_bf16 v[36:39], v[146:149], v[170:173], 0
	v_mfma_f32_16x16x32_bf16 v[28:31], v[134:137], v[178:181], 0
	v_mfma_f32_16x16x32_bf16 v[20:23], v[146:149], v[178:181], 0
	v_mfma_f32_16x16x32_bf16 v[12:15], v[134:137], v[186:189], 0
	v_mfma_f32_16x16x32_bf16 v[4:7], v[146:149], v[186:189], 0
	v_mfma_f32_16x16x32_bf16 v[60:63], v[142:145], v[166:169], v[60:63]
	v_mfma_f32_16x16x32_bf16 v[52:55], v[150:153], v[166:169], v[52:55]
	v_mfma_f32_16x16x32_bf16 v[44:47], v[142:145], v[174:177], v[44:47]
	v_mfma_f32_16x16x32_bf16 v[36:39], v[150:153], v[174:177], v[36:39]
	v_mfma_f32_16x16x32_bf16 v[28:31], v[142:145], v[182:185], v[28:31]
	v_mfma_f32_16x16x32_bf16 v[20:23], v[150:153], v[182:185], v[20:23]
	v_mfma_f32_16x16x32_bf16 v[12:15], v[142:145], v[214:217], v[12:15]
	v_mfma_f32_16x16x32_bf16 v[4:7], v[150:153], v[214:217], v[4:7]
	s_setprio 0
	s_barrier
	s_add_u32 s78, s54, 0x40000
	s_addc_u32 s79, s55, 0
	s_add_i32 s77, s80, s53
	s_mov_b32 m0, s77
	s_nop 0
	global_load_lds_dwordx4 v156, s[78:79]
	s_add_i32 m0, s77, 0x2000
	s_nop 0
	global_load_lds_dwordx4 v128, s[78:79]
	s_waitcnt vmcnt(6)
	s_barrier
	s_setprio 1
	v_mfma_f32_16x16x32_bf16 v[56:59], v[218:221], v[162:165], 0
	v_mfma_f32_16x16x32_bf16 v[48:51], v[226:229], v[162:165], 0
	v_mfma_f32_16x16x32_bf16 v[40:43], v[218:221], v[170:173], 0
	v_mfma_f32_16x16x32_bf16 v[32:35], v[226:229], v[170:173], 0
	v_mfma_f32_16x16x32_bf16 v[24:27], v[218:221], v[178:181], 0
	v_mfma_f32_16x16x32_bf16 v[16:19], v[226:229], v[178:181], 0
	v_mfma_f32_16x16x32_bf16 v[8:11], v[218:221], v[186:189], 0
	v_mfma_f32_16x16x32_bf16 v[0:3], v[226:229], v[186:189], 0
	v_mfma_f32_16x16x32_bf16 v[56:59], v[222:225], v[166:169], v[56:59]
	v_mfma_f32_16x16x32_bf16 v[48:51], v[230:233], v[166:169], v[48:51]
	v_mfma_f32_16x16x32_bf16 v[40:43], v[222:225], v[174:177], v[40:43]
	v_mfma_f32_16x16x32_bf16 v[32:35], v[230:233], v[174:177], v[32:35]
	v_mfma_f32_16x16x32_bf16 v[24:27], v[222:225], v[182:185], v[24:27]
	v_mfma_f32_16x16x32_bf16 v[16:19], v[230:233], v[182:185], v[16:19]
	v_mfma_f32_16x16x32_bf16 v[8:11], v[222:225], v[214:217], v[8:11]
	v_mfma_f32_16x16x32_bf16 v[0:3], v[230:233], v[214:217], v[0:3]
	s_setprio 0
	s_add_i32 s77, 0, 0x18000
	v_add_u32_e32 v150, s77, v139
	s_barrier
	ds_read_b128 v[134:137], v150
	ds_read_b128 v[142:145], v150 offset:1024
	ds_read_b128 v[146:149], v150 offset:2048
	ds_read_b128 v[150:153], v150 offset:3072
	s_add_u32 s2, s2, 0x40000
	s_addc_u32 s3, s3, 0
	s_mov_b32 m0, s62
	ds_read_b128 v[162:165], v141 offset:32768
	ds_read_b128 v[166:169], v141 offset:33792
	ds_read_b128 v[170:173], v141 offset:34816
	ds_read_b128 v[174:177], v141 offset:35840
	ds_read_b128 v[178:181], v141 offset:36864
	ds_read_b128 v[182:185], v141 offset:37888
	ds_read_b128 v[186:189], v141 offset:38912
	ds_read_b128 v[214:217], v141 offset:39936
	global_load_lds_dwordx4 v156, s[2:3]
	s_mov_b32 m0, s63
	s_nop 0
	global_load_lds_dwordx4 v128, s[2:3]
	s_waitcnt lgkmcnt(8)
	s_barrier
	s_waitcnt lgkmcnt(0)
	s_setprio 1
	s_waitcnt lgkmcnt(0)
	v_mfma_f32_16x16x32_bf16 v[124:127], v[134:137], v[162:165], v[124:127]
	v_mfma_f32_16x16x32_bf16 v[116:119], v[146:149], v[162:165], v[116:119]
	v_mfma_f32_16x16x32_bf16 v[108:111], v[134:137], v[170:173], v[108:111]
	v_mfma_f32_16x16x32_bf16 v[100:103], v[146:149], v[170:173], v[100:103]
	v_mfma_f32_16x16x32_bf16 v[92:95], v[134:137], v[178:181], v[92:95]
	v_mfma_f32_16x16x32_bf16 v[84:87], v[146:149], v[178:181], v[84:87]
	v_mfma_f32_16x16x32_bf16 v[76:79], v[134:137], v[186:189], v[76:79]
	v_mfma_f32_16x16x32_bf16 v[68:71], v[146:149], v[186:189], v[68:71]
	v_mfma_f32_16x16x32_bf16 v[124:127], v[142:145], v[166:169], v[124:127]
	v_mfma_f32_16x16x32_bf16 v[116:119], v[150:153], v[166:169], v[116:119]
	v_mfma_f32_16x16x32_bf16 v[108:111], v[142:145], v[174:177], v[108:111]
	v_mfma_f32_16x16x32_bf16 v[100:103], v[150:153], v[174:177], v[100:103]
	v_mfma_f32_16x16x32_bf16 v[92:95], v[142:145], v[182:185], v[92:95]
	v_mfma_f32_16x16x32_bf16 v[84:87], v[150:153], v[182:185], v[84:87]
	v_mfma_f32_16x16x32_bf16 v[76:79], v[142:145], v[214:217], v[76:79]
	v_mfma_f32_16x16x32_bf16 v[68:71], v[150:153], v[214:217], v[68:71]
	s_setprio 0
	s_barrier
	s_add_i32 s78, 0, 0x1c000
	s_add_i32 s2, s77, s53
	v_add_u32_e32 v161, s78, v139
	v_lshl_add_u64 v[154:155], v[154:155], 0, s[50:51]
	s_mov_b32 m0, s2
	ds_read_b128 v[218:221], v161
	ds_read_b128 v[222:225], v161 offset:1024
	ds_read_b128 v[226:229], v161 offset:2048
	ds_read_b128 v[230:233], v161 offset:3072
	global_load_lds_dwordx4 v[154:155], off
	v_lshl_add_u64 v[154:155], v[206:207], 0, s[50:51]
	s_add_i32 m0, s2, 0x2000
	s_nop 0
	global_load_lds_dwordx4 v[154:155], off
	s_barrier
	s_waitcnt lgkmcnt(0)
	s_setprio 1
	s_waitcnt lgkmcnt(0)
	v_mfma_f32_16x16x32_bf16 v[120:123], v[218:221], v[162:165], v[120:123]
	v_mfma_f32_16x16x32_bf16 v[112:115], v[226:229], v[162:165], v[112:115]
	v_mfma_f32_16x16x32_bf16 v[104:107], v[218:221], v[170:173], v[104:107]
	v_mfma_f32_16x16x32_bf16 v[96:99], v[226:229], v[170:173], v[96:99]
	v_mfma_f32_16x16x32_bf16 v[88:91], v[218:221], v[178:181], v[88:91]
	v_mfma_f32_16x16x32_bf16 v[80:83], v[226:229], v[178:181], v[80:83]
	v_mfma_f32_16x16x32_bf16 v[72:75], v[218:221], v[186:189], v[72:75]
	v_mfma_f32_16x16x32_bf16 v[64:67], v[226:229], v[186:189], v[64:67]
	v_mfma_f32_16x16x32_bf16 v[120:123], v[222:225], v[166:169], v[120:123]
	v_mfma_f32_16x16x32_bf16 v[112:115], v[230:233], v[166:169], v[112:115]
	v_mfma_f32_16x16x32_bf16 v[104:107], v[222:225], v[174:177], v[104:107]
	v_mfma_f32_16x16x32_bf16 v[96:99], v[230:233], v[174:177], v[96:99]
	v_mfma_f32_16x16x32_bf16 v[88:91], v[222:225], v[182:185], v[88:91]
	v_mfma_f32_16x16x32_bf16 v[80:83], v[230:233], v[182:185], v[80:83]
	v_mfma_f32_16x16x32_bf16 v[72:75], v[222:225], v[214:217], v[72:75]
	v_mfma_f32_16x16x32_bf16 v[64:67], v[230:233], v[214:217], v[64:67]
	s_setprio 0
	s_mov_b32 m0, s66
	v_lshl_add_u64 v[154:155], v[208:209], 0, s[50:51]
	s_barrier
	ds_read_b128 v[162:165], v141 offset:49152
	ds_read_b128 v[166:169], v141 offset:50176
	ds_read_b128 v[170:173], v141 offset:51200
	ds_read_b128 v[174:177], v141 offset:52224
	ds_read_b128 v[178:181], v141 offset:53248
	ds_read_b128 v[182:185], v141 offset:54272
	ds_read_b128 v[186:189], v141 offset:55296
	ds_read_b128 v[214:217], v141 offset:56320
	global_load_lds_dwordx4 v[154:155], off
	v_lshl_add_u64 v[154:155], v[234:235], 0, s[50:51]
	s_mov_b32 m0, s67
	s_nop 0
	global_load_lds_dwordx4 v[154:155], off
	s_barrier
	s_waitcnt lgkmcnt(0)
	s_setprio 1
	s_waitcnt lgkmcnt(0)
	v_mfma_f32_16x16x32_bf16 v[60:63], v[134:137], v[162:165], v[60:63]
	v_mfma_f32_16x16x32_bf16 v[52:55], v[146:149], v[162:165], v[52:55]
	v_mfma_f32_16x16x32_bf16 v[44:47], v[134:137], v[170:173], v[44:47]
	v_mfma_f32_16x16x32_bf16 v[36:39], v[146:149], v[170:173], v[36:39]
	v_mfma_f32_16x16x32_bf16 v[28:31], v[134:137], v[178:181], v[28:31]
	v_mfma_f32_16x16x32_bf16 v[20:23], v[146:149], v[178:181], v[20:23]
	v_mfma_f32_16x16x32_bf16 v[12:15], v[134:137], v[186:189], v[12:15]
	v_mfma_f32_16x16x32_bf16 v[4:7], v[146:149], v[186:189], v[4:7]
	v_mfma_f32_16x16x32_bf16 v[60:63], v[142:145], v[166:169], v[60:63]
	v_mfma_f32_16x16x32_bf16 v[52:55], v[150:153], v[166:169], v[52:55]
	v_mfma_f32_16x16x32_bf16 v[44:47], v[142:145], v[174:177], v[44:47]
	v_mfma_f32_16x16x32_bf16 v[36:39], v[150:153], v[174:177], v[36:39]
	v_mfma_f32_16x16x32_bf16 v[28:31], v[142:145], v[182:185], v[28:31]
	v_mfma_f32_16x16x32_bf16 v[20:23], v[150:153], v[182:185], v[20:23]
	v_mfma_f32_16x16x32_bf16 v[12:15], v[142:145], v[214:217], v[12:15]
	v_mfma_f32_16x16x32_bf16 v[4:7], v[150:153], v[214:217], v[4:7]
	s_setprio 0
	s_barrier
	s_add_u32 s2, s54, 0x40080
	s_addc_u32 s3, s55, 0
	s_add_i32 s54, s78, s53
	s_mov_b32 m0, s54
	s_nop 0
	global_load_lds_dwordx4 v156, s[2:3]
	s_add_i32 m0, s54, 0x2000
	s_nop 0
	global_load_lds_dwordx4 v128, s[2:3]
	s_waitcnt vmcnt(6)
	s_barrier
	s_setprio 1
	v_mfma_f32_16x16x32_bf16 v[56:59], v[218:221], v[162:165], v[56:59]
	v_mfma_f32_16x16x32_bf16 v[48:51], v[226:229], v[162:165], v[48:51]
	v_mfma_f32_16x16x32_bf16 v[40:43], v[218:221], v[170:173], v[40:43]
	v_mfma_f32_16x16x32_bf16 v[32:35], v[226:229], v[170:173], v[32:35]
	v_mfma_f32_16x16x32_bf16 v[24:27], v[218:221], v[178:181], v[24:27]
	v_mfma_f32_16x16x32_bf16 v[16:19], v[226:229], v[178:181], v[16:19]
	v_mfma_f32_16x16x32_bf16 v[8:11], v[218:221], v[186:189], v[8:11]
	v_mfma_f32_16x16x32_bf16 v[0:3], v[226:229], v[186:189], v[0:3]
	v_mfma_f32_16x16x32_bf16 v[56:59], v[222:225], v[166:169], v[56:59]
	v_mfma_f32_16x16x32_bf16 v[48:51], v[230:233], v[166:169], v[48:51]
	v_mfma_f32_16x16x32_bf16 v[40:43], v[222:225], v[174:177], v[40:43]
	v_mfma_f32_16x16x32_bf16 v[32:35], v[230:233], v[174:177], v[32:35]
	v_mfma_f32_16x16x32_bf16 v[24:27], v[222:225], v[182:185], v[24:27]
	v_mfma_f32_16x16x32_bf16 v[16:19], v[230:233], v[182:185], v[16:19]
	v_mfma_f32_16x16x32_bf16 v[8:11], v[222:225], v[214:217], v[8:11]
	v_mfma_f32_16x16x32_bf16 v[0:3], v[230:233], v[214:217], v[0:3]
	s_setprio 0
	s_add_i32 s73, s73, 2
	s_add_u32 s43, s43, 0x100
	s_addc_u32 s69, s69, 0
	s_add_u32 s6, s6, 0x100
	s_addc_u32 s7, s7, 0
	s_cmp_gt_u32 s73, 13
	s_barrier
	s_cbranch_scc1 .Lpost_555
.LBB0_555:
	s_add_u32 s2, s6, 0xfffc0080
	s_addc_u32 s3, s7, -1
	s_add_i32 s77, 0, 0x10000
	v_add_u32_e32 v150, s77, v139
	ds_read_b128 v[134:137], v150
	ds_read_b128 v[142:145], v150 offset:1024
	ds_read_b128 v[146:149], v150 offset:2048
	ds_read_b128 v[150:153], v150 offset:3072
	s_cmp_eq_u32 s73, 12
	s_cselect_b32 s3, s10, s3
	s_cselect_b32 s2, s24, s2
	s_cselect_b32 s55, s25, s69
	s_cselect_b32 s54, s41, s43
	s_add_i32 m0, s47, 0xc000
	ds_read_b128 v[162:165], v141
	ds_read_b128 v[166:169], v141 offset:1024
	ds_read_b128 v[170:173], v141 offset:2048
	ds_read_b128 v[174:177], v141 offset:3072
	ds_read_b128 v[178:181], v141 offset:4096
	ds_read_b128 v[182:185], v141 offset:5120
	ds_read_b128 v[186:189], v141 offset:6144
	ds_read_b128 v[214:217], v141 offset:7168
	global_load_lds_dwordx4 v132, s[6:7]
	s_add_i32 m0, s47, 0xe000
	s_nop 0
	global_load_lds_dwordx4 v130, s[6:7]
	s_waitcnt lgkmcnt(8)
	s_barrier
	s_waitcnt lgkmcnt(0)
	s_setprio 1
	s_waitcnt lgkmcnt(0)
	v_mfma_f32_16x16x32_bf16 v[124:127], v[134:137], v[162:165], v[124:127]
	v_mfma_f32_16x16x32_bf16 v[116:119], v[146:149], v[162:165], v[116:119]
	v_mfma_f32_16x16x32_bf16 v[108:111], v[134:137], v[170:173], v[108:111]
	v_mfma_f32_16x16x32_bf16 v[100:103], v[146:149], v[170:173], v[100:103]
	v_mfma_f32_16x16x32_bf16 v[92:95], v[134:137], v[178:181], v[92:95]
	v_mfma_f32_16x16x32_bf16 v[84:87], v[146:149], v[178:181], v[84:87]
	v_mfma_f32_16x16x32_bf16 v[76:79], v[134:137], v[186:189], v[76:79]
	v_mfma_f32_16x16x32_bf16 v[68:71], v[146:149], v[186:189], v[68:71]
	v_mfma_f32_16x16x32_bf16 v[124:127], v[142:145], v[166:169], v[124:127]
	v_mfma_f32_16x16x32_bf16 v[116:119], v[150:153], v[166:169], v[116:119]
	v_mfma_f32_16x16x32_bf16 v[108:111], v[142:145], v[174:177], v[108:111]
	v_mfma_f32_16x16x32_bf16 v[100:103], v[150:153], v[174:177], v[100:103]
	v_mfma_f32_16x16x32_bf16 v[92:95], v[142:145], v[182:185], v[92:95]
	v_mfma_f32_16x16x32_bf16 v[84:87], v[150:153], v[182:185], v[84:87]
	v_mfma_f32_16x16x32_bf16 v[76:79], v[142:145], v[214:217], v[76:79]
	v_mfma_f32_16x16x32_bf16 v[68:71], v[150:153], v[214:217], v[68:71]
	s_setprio 0
	s_barrier
	s_add_i32 s80, 0, 0x14000
	v_add_u32_e32 v154, s80, v139
	s_add_i32 s77, s77, s53
	ds_read_b128 v[218:221], v154
	ds_read_b128 v[222:225], v154 offset:1024
	ds_read_b128 v[226:229], v154 offset:2048
	ds_read_b128 v[230:233], v154 offset:3072
	v_lshl_add_u64 v[154:155], s[54:55], 0, v[156:157]
	s_mov_b32 m0, s77
	v_lshl_add_u64 v[206:207], s[54:55], 0, v[128:129]
	global_load_lds_dwordx4 v[154:155], off
	s_add_i32 m0, s77, 0x2000
	s_nop 0
	global_load_lds_dwordx4 v[206:207], off
	s_barrier
	s_waitcnt lgkmcnt(0)
	s_setprio 1
	s_waitcnt lgkmcnt(0)
	v_mfma_f32_16x16x32_bf16 v[120:123], v[218:221], v[162:165], v[120:123]
	v_mfma_f32_16x16x32_bf16 v[112:115], v[226:229], v[162:165], v[112:115]
	v_mfma_f32_16x16x32_bf16 v[104:107], v[218:221], v[170:173], v[104:107]
	v_mfma_f32_16x16x32_bf16 v[96:99], v[226:229], v[170:173], v[96:99]
	v_mfma_f32_16x16x32_bf16 v[88:91], v[218:221], v[178:181], v[88:91]
	v_mfma_f32_16x16x32_bf16 v[80:83], v[226:229], v[178:181], v[80:83]
	v_mfma_f32_16x16x32_bf16 v[72:75], v[218:221], v[186:189], v[72:75]
	v_mfma_f32_16x16x32_bf16 v[64:67], v[226:229], v[186:189], v[64:67]
	v_mfma_f32_16x16x32_bf16 v[120:123], v[222:225], v[166:169], v[120:123]
	v_mfma_f32_16x16x32_bf16 v[112:115], v[230:233], v[166:169], v[112:115]
	v_mfma_f32_16x16x32_bf16 v[104:107], v[222:225], v[174:177], v[104:107]
	v_mfma_f32_16x16x32_bf16 v[96:99], v[230:233], v[174:177], v[96:99]
	v_mfma_f32_16x16x32_bf16 v[88:91], v[222:225], v[182:185], v[88:91]
	v_mfma_f32_16x16x32_bf16 v[80:83], v[230:233], v[182:185], v[80:83]
	v_mfma_f32_16x16x32_bf16 v[72:75], v[222:225], v[214:217], v[72:75]
	v_mfma_f32_16x16x32_bf16 v[64:67], v[230:233], v[214:217], v[64:67]
	s_setprio 0
	s_mov_b32 m0, s47
	v_lshl_add_u64 v[208:209], s[2:3], 0, v[156:157]
	s_barrier
	ds_read_b128 v[162:165], v141 offset:16384
	ds_read_b128 v[166:169], v141 offset:17408
	ds_read_b128 v[170:173], v141 offset:18432
	ds_read_b128 v[174:177], v141 offset:19456
	ds_read_b128 v[178:181], v141 offset:20480
	ds_read_b128 v[182:185], v141 offset:21504
	ds_read_b128 v[186:189], v141 offset:22528
	ds_read_b128 v[214:217], v141 offset:23552
	global_load_lds_dwordx4 v[208:209], off
	v_lshl_add_u64 v[234:235], s[2:3], 0, v[128:129]
	s_mov_b32 m0, s49
	s_nop 0
	global_load_lds_dwordx4 v[234:235], off
	s_barrier
	s_waitcnt lgkmcnt(0)
	s_setprio 1
	s_waitcnt lgkmcnt(0)
	v_mfma_f32_16x16x32_bf16 v[60:63], v[134:137], v[162:165], v[60:63]
	v_mfma_f32_16x16x32_bf16 v[52:55], v[146:149], v[162:165], v[52:55]
	v_mfma_f32_16x16x32_bf16 v[44:47], v[134:137], v[170:173], v[44:47]
	v_mfma_f32_16x16x32_bf16 v[36:39], v[146:149], v[170:173], v[36:39]
	v_mfma_f32_16x16x32_bf16 v[28:31], v[134:137], v[178:181], v[28:31]
	v_mfma_f32_16x16x32_bf16 v[20:23], v[146:149], v[178:181], v[20:23]
	v_mfma_f32_16x16x32_bf16 v[12:15], v[134:137], v[186:189], v[12:15]
	v_mfma_f32_16x16x32_bf16 v[4:7], v[146:149], v[186:189], v[4:7]
	v_mfma_f32_16x16x32_bf16 v[60:63], v[142:145], v[166:169], v[60:63]
	v_mfma_f32_16x16x32_bf16 v[52:55], v[150:153], v[166:169], v[52:55]
	v_mfma_f32_16x16x32_bf16 v[44:47], v[142:145], v[174:177], v[44:47]
	v_mfma_f32_16x16x32_bf16 v[36:39], v[150:153], v[174:177], v[36:39]
	v_mfma_f32_16x16x32_bf16 v[28:31], v[142:145], v[182:185], v[28:31]
	v_mfma_f32_16x16x32_bf16 v[20:23], v[150:153], v[182:185], v[20:23]
	v_mfma_f32_16x16x32_bf16 v[12:15], v[142:145], v[214:217], v[12:15]
	v_mfma_f32_16x16x32_bf16 v[4:7], v[150:153], v[214:217], v[4:7]
	s_setprio 0
	s_barrier
	s_add_u32 s78, s54, 0x40000
	s_addc_u32 s79, s55, 0
	s_add_i32 s77, s80, s53
	s_mov_b32 m0, s77
	s_nop 0
	global_load_lds_dwordx4 v156, s[78:79]
	s_add_i32 m0, s77, 0x2000
	s_nop 0
	global_load_lds_dwordx4 v128, s[78:79]
	s_waitcnt vmcnt(6)
	s_barrier
	s_setprio 1
	v_mfma_f32_16x16x32_bf16 v[56:59], v[218:221], v[162:165], v[56:59]
	v_mfma_f32_16x16x32_bf16 v[48:51], v[226:229], v[162:165], v[48:51]
	v_mfma_f32_16x16x32_bf16 v[40:43], v[218:221], v[170:173], v[40:43]
	v_mfma_f32_16x16x32_bf16 v[32:35], v[226:229], v[170:173], v[32:35]
	v_mfma_f32_16x16x32_bf16 v[24:27], v[218:221], v[178:181], v[24:27]
	v_mfma_f32_16x16x32_bf16 v[16:19], v[226:229], v[178:181], v[16:19]
	v_mfma_f32_16x16x32_bf16 v[8:11], v[218:221], v[186:189], v[8:11]
	v_mfma_f32_16x16x32_bf16 v[0:3], v[226:229], v[186:189], v[0:3]
	v_mfma_f32_16x16x32_bf16 v[56:59], v[222:225], v[166:169], v[56:59]
	v_mfma_f32_16x16x32_bf16 v[48:51], v[230:233], v[166:169], v[48:51]
	v_mfma_f32_16x16x32_bf16 v[40:43], v[222:225], v[174:177], v[40:43]
	v_mfma_f32_16x16x32_bf16 v[32:35], v[230:233], v[174:177], v[32:35]
	v_mfma_f32_16x16x32_bf16 v[24:27], v[222:225], v[182:185], v[24:27]
	v_mfma_f32_16x16x32_bf16 v[16:19], v[230:233], v[182:185], v[16:19]
	v_mfma_f32_16x16x32_bf16 v[8:11], v[222:225], v[214:217], v[8:11]
	v_mfma_f32_16x16x32_bf16 v[0:3], v[230:233], v[214:217], v[0:3]
	s_setprio 0
	s_add_i32 s77, 0, 0x18000
	v_add_u32_e32 v150, s77, v139
	s_barrier
	ds_read_b128 v[134:137], v150
	ds_read_b128 v[142:145], v150 offset:1024
	ds_read_b128 v[146:149], v150 offset:2048
	ds_read_b128 v[150:153], v150 offset:3072
	s_add_u32 s2, s2, 0x40000
	s_addc_u32 s3, s3, 0
	s_mov_b32 m0, s62
	ds_read_b128 v[162:165], v141 offset:32768
	ds_read_b128 v[166:169], v141 offset:33792
	ds_read_b128 v[170:173], v141 offset:34816
	ds_read_b128 v[174:177], v141 offset:35840
	ds_read_b128 v[178:181], v141 offset:36864
	ds_read_b128 v[182:185], v141 offset:37888
	ds_read_b128 v[186:189], v141 offset:38912
	ds_read_b128 v[214:217], v141 offset:39936
	global_load_lds_dwordx4 v156, s[2:3]
	s_mov_b32 m0, s63
	s_nop 0
	global_load_lds_dwordx4 v128, s[2:3]
	s_waitcnt lgkmcnt(8)
	s_barrier
	s_waitcnt lgkmcnt(0)
	s_setprio 1
	s_waitcnt lgkmcnt(0)
	v_mfma_f32_16x16x32_bf16 v[124:127], v[134:137], v[162:165], v[124:127]
	v_mfma_f32_16x16x32_bf16 v[116:119], v[146:149], v[162:165], v[116:119]
	v_mfma_f32_16x16x32_bf16 v[108:111], v[134:137], v[170:173], v[108:111]
	v_mfma_f32_16x16x32_bf16 v[100:103], v[146:149], v[170:173], v[100:103]
	v_mfma_f32_16x16x32_bf16 v[92:95], v[134:137], v[178:181], v[92:95]
	v_mfma_f32_16x16x32_bf16 v[84:87], v[146:149], v[178:181], v[84:87]
	v_mfma_f32_16x16x32_bf16 v[76:79], v[134:137], v[186:189], v[76:79]
	v_mfma_f32_16x16x32_bf16 v[68:71], v[146:149], v[186:189], v[68:71]
	v_mfma_f32_16x16x32_bf16 v[124:127], v[142:145], v[166:169], v[124:127]
	v_mfma_f32_16x16x32_bf16 v[116:119], v[150:153], v[166:169], v[116:119]
	v_mfma_f32_16x16x32_bf16 v[108:111], v[142:145], v[174:177], v[108:111]
	v_mfma_f32_16x16x32_bf16 v[100:103], v[150:153], v[174:177], v[100:103]
	v_mfma_f32_16x16x32_bf16 v[92:95], v[142:145], v[182:185], v[92:95]
	v_mfma_f32_16x16x32_bf16 v[84:87], v[150:153], v[182:185], v[84:87]
	v_mfma_f32_16x16x32_bf16 v[76:79], v[142:145], v[214:217], v[76:79]
	v_mfma_f32_16x16x32_bf16 v[68:71], v[150:153], v[214:217], v[68:71]
	s_setprio 0
	s_barrier
	s_add_i32 s78, 0, 0x1c000
	s_add_i32 s2, s77, s53
	v_add_u32_e32 v161, s78, v139
	v_lshl_add_u64 v[154:155], v[154:155], 0, s[50:51]
	s_mov_b32 m0, s2
	ds_read_b128 v[218:221], v161
	ds_read_b128 v[222:225], v161 offset:1024
	ds_read_b128 v[226:229], v161 offset:2048
	ds_read_b128 v[230:233], v161 offset:3072
	global_load_lds_dwordx4 v[154:155], off
	v_lshl_add_u64 v[154:155], v[206:207], 0, s[50:51]
	s_add_i32 m0, s2, 0x2000
	s_nop 0
	global_load_lds_dwordx4 v[154:155], off
	s_barrier
	s_waitcnt lgkmcnt(0)
	s_setprio 1
	s_waitcnt lgkmcnt(0)
	v_mfma_f32_16x16x32_bf16 v[120:123], v[218:221], v[162:165], v[120:123]
	v_mfma_f32_16x16x32_bf16 v[112:115], v[226:229], v[162:165], v[112:115]
	v_mfma_f32_16x16x32_bf16 v[104:107], v[218:221], v[170:173], v[104:107]
	v_mfma_f32_16x16x32_bf16 v[96:99], v[226:229], v[170:173], v[96:99]
	v_mfma_f32_16x16x32_bf16 v[88:91], v[218:221], v[178:181], v[88:91]
	v_mfma_f32_16x16x32_bf16 v[80:83], v[226:229], v[178:181], v[80:83]
	v_mfma_f32_16x16x32_bf16 v[72:75], v[218:221], v[186:189], v[72:75]
	v_mfma_f32_16x16x32_bf16 v[64:67], v[226:229], v[186:189], v[64:67]
	v_mfma_f32_16x16x32_bf16 v[120:123], v[222:225], v[166:169], v[120:123]
	v_mfma_f32_16x16x32_bf16 v[112:115], v[230:233], v[166:169], v[112:115]
	v_mfma_f32_16x16x32_bf16 v[104:107], v[222:225], v[174:177], v[104:107]
	v_mfma_f32_16x16x32_bf16 v[96:99], v[230:233], v[174:177], v[96:99]
	v_mfma_f32_16x16x32_bf16 v[88:91], v[222:225], v[182:185], v[88:91]
	v_mfma_f32_16x16x32_bf16 v[80:83], v[230:233], v[182:185], v[80:83]
	v_mfma_f32_16x16x32_bf16 v[72:75], v[222:225], v[214:217], v[72:75]
	v_mfma_f32_16x16x32_bf16 v[64:67], v[230:233], v[214:217], v[64:67]
	s_setprio 0
	s_mov_b32 m0, s66
	v_lshl_add_u64 v[154:155], v[208:209], 0, s[50:51]
	s_barrier
	ds_read_b128 v[162:165], v141 offset:49152
	ds_read_b128 v[166:169], v141 offset:50176
	ds_read_b128 v[170:173], v141 offset:51200
	ds_read_b128 v[174:177], v141 offset:52224
	ds_read_b128 v[178:181], v141 offset:53248
	ds_read_b128 v[182:185], v141 offset:54272
	ds_read_b128 v[186:189], v141 offset:55296
	ds_read_b128 v[214:217], v141 offset:56320
	global_load_lds_dwordx4 v[154:155], off
	v_lshl_add_u64 v[154:155], v[234:235], 0, s[50:51]
	s_mov_b32 m0, s67
	s_nop 0
	global_load_lds_dwordx4 v[154:155], off
	s_barrier
	s_waitcnt lgkmcnt(0)
	s_setprio 1
	s_waitcnt lgkmcnt(0)
	v_mfma_f32_16x16x32_bf16 v[60:63], v[134:137], v[162:165], v[60:63]
	v_mfma_f32_16x16x32_bf16 v[52:55], v[146:149], v[162:165], v[52:55]
	v_mfma_f32_16x16x32_bf16 v[44:47], v[134:137], v[170:173], v[44:47]
	v_mfma_f32_16x16x32_bf16 v[36:39], v[146:149], v[170:173], v[36:39]
	v_mfma_f32_16x16x32_bf16 v[28:31], v[134:137], v[178:181], v[28:31]
	v_mfma_f32_16x16x32_bf16 v[20:23], v[146:149], v[178:181], v[20:23]
	v_mfma_f32_16x16x32_bf16 v[12:15], v[134:137], v[186:189], v[12:15]
	v_mfma_f32_16x16x32_bf16 v[4:7], v[146:149], v[186:189], v[4:7]
	v_mfma_f32_16x16x32_bf16 v[60:63], v[142:145], v[166:169], v[60:63]
	v_mfma_f32_16x16x32_bf16 v[52:55], v[150:153], v[166:169], v[52:55]
	v_mfma_f32_16x16x32_bf16 v[44:47], v[142:145], v[174:177], v[44:47]
	v_mfma_f32_16x16x32_bf16 v[36:39], v[150:153], v[174:177], v[36:39]
	v_mfma_f32_16x16x32_bf16 v[28:31], v[142:145], v[182:185], v[28:31]
	v_mfma_f32_16x16x32_bf16 v[20:23], v[150:153], v[182:185], v[20:23]
	v_mfma_f32_16x16x32_bf16 v[12:15], v[142:145], v[214:217], v[12:15]
	v_mfma_f32_16x16x32_bf16 v[4:7], v[150:153], v[214:217], v[4:7]
	s_setprio 0
	s_barrier
	s_add_u32 s2, s54, 0x40080
	s_addc_u32 s3, s55, 0
	s_add_i32 s54, s78, s53
	s_mov_b32 m0, s54
	s_nop 0
	global_load_lds_dwordx4 v156, s[2:3]
	s_add_i32 m0, s54, 0x2000
	s_nop 0
	global_load_lds_dwordx4 v128, s[2:3]
	s_waitcnt vmcnt(6)
	s_barrier
	s_setprio 1
	v_mfma_f32_16x16x32_bf16 v[56:59], v[218:221], v[162:165], v[56:59]
	v_mfma_f32_16x16x32_bf16 v[48:51], v[226:229], v[162:165], v[48:51]
	v_mfma_f32_16x16x32_bf16 v[40:43], v[218:221], v[170:173], v[40:43]
	v_mfma_f32_16x16x32_bf16 v[32:35], v[226:229], v[170:173], v[32:35]
	v_mfma_f32_16x16x32_bf16 v[24:27], v[218:221], v[178:181], v[24:27]
	v_mfma_f32_16x16x32_bf16 v[16:19], v[226:229], v[178:181], v[16:19]
	v_mfma_f32_16x16x32_bf16 v[8:11], v[218:221], v[186:189], v[8:11]
	v_mfma_f32_16x16x32_bf16 v[0:3], v[226:229], v[186:189], v[0:3]
	v_mfma_f32_16x16x32_bf16 v[56:59], v[222:225], v[166:169], v[56:59]
	v_mfma_f32_16x16x32_bf16 v[48:51], v[230:233], v[166:169], v[48:51]
	v_mfma_f32_16x16x32_bf16 v[40:43], v[222:225], v[174:177], v[40:43]
	v_mfma_f32_16x16x32_bf16 v[32:35], v[230:233], v[174:177], v[32:35]
	v_mfma_f32_16x16x32_bf16 v[24:27], v[222:225], v[182:185], v[24:27]
	v_mfma_f32_16x16x32_bf16 v[16:19], v[230:233], v[182:185], v[16:19]
	v_mfma_f32_16x16x32_bf16 v[8:11], v[222:225], v[214:217], v[8:11]
	v_mfma_f32_16x16x32_bf16 v[0:3], v[230:233], v[214:217], v[0:3]
	s_setprio 0
	s_add_i32 s73, s73, 2
	s_add_u32 s43, s43, 0x100
	s_addc_u32 s69, s69, 0
	s_add_u32 s6, s6, 0x100
	s_addc_u32 s7, s7, 0
	s_cmp_gt_u32 s73, 13
	s_barrier
	s_cbranch_scc0 .LBB0_555
